# attention tile loop, 7.12-style trim: the s_and_b64 that only re-derived SCC after s_cmpk_eq/s_cselect_b64 deleted; on top of v058
# speedup vs baseline: 1.0014x; 1.0007x over previous
.LBB0_873:
	s_cmpk_eq_i32 s71, 0xffd0
	s_cselect_b64 s[34:35], -1, 0
	s_cselect_b32 s84, 0, s71
	s_cmp_gt_i32 s84, s29
	s_cselect_b64 s[4:5], -1, 0
	s_or_b64 s[4:5], s[58:59], s[4:5]
	s_and_b64 vcc, exec, s[4:5]
	s_cbranch_vccnz .LBB0_883
	s_add_i32 s4, s84, 63
	s_cmp_gt_i32 s4, s95
	s_cselect_b64 s[4:5], -1, 0
	s_or_b64 s[4:5], s[34:35], s[4:5]
	s_and_b64 vcc, exec, s[4:5]
	s_cbranch_vccnz .Lattn_orig
	ds_read_b128 v[88:91], v221
	ds_read_b128 v[92:95], v221 offset:64
	ds_read_b128 v[164:167], v221 offset:576
	ds_read_b128 v[168:171], v221 offset:640
	ds_read_b128 v[172:175], v221 offset:4608
	ds_read_b128 v[236:239], v221 offset:4672
	ds_read_b128 v[240:243], v221 offset:5184
	ds_read_b128 v[160:163], v221 offset:5248
	v_readlane_b32 s4, v84, 0
	v_readlane_b32 s5, v75, 63
	v_pk_add_f32 v[116:117], v[140:141], v[84:85] neg_lo:[0,1] neg_hi:[0,1]
	v_pk_add_f32 v[118:119], v[140:141], v[86:87] neg_lo:[0,1] neg_hi:[0,1]
	v_pk_add_f32 v[100:101], v[142:143], v[84:85] neg_lo:[0,1] neg_hi:[0,1]
	v_pk_add_f32 v[102:103], v[142:143], v[86:87] neg_lo:[0,1] neg_hi:[0,1]
	v_pk_add_f32 v[112:113], v[140:141], v[76:77] neg_lo:[0,1] neg_hi:[0,1]
	v_pk_add_f32 v[114:115], v[140:141], v[78:79] neg_lo:[0,1] neg_hi:[0,1]
	v_pk_add_f32 v[96:97], v[142:143], v[76:77] neg_lo:[0,1] neg_hi:[0,1]
	v_pk_add_f32 v[98:99], v[142:143], v[78:79] neg_lo:[0,1] neg_hi:[0,1]
	v_pk_add_f32 v[108:109], v[140:141], v[80:81] neg_lo:[0,1] neg_hi:[0,1]
	v_pk_add_f32 v[110:111], v[140:141], v[82:83] neg_lo:[0,1] neg_hi:[0,1]
	v_pk_add_f32 v[244:245], v[142:143], v[80:81] neg_lo:[0,1] neg_hi:[0,1]
	v_pk_add_f32 v[246:247], v[142:143], v[82:83] neg_lo:[0,1] neg_hi:[0,1]
	v_pk_add_f32 v[104:105], v[140:141], v[72:73] neg_lo:[0,1] neg_hi:[0,1]
	v_pk_add_f32 v[106:107], v[140:141], v[74:75] neg_lo:[0,1] neg_hi:[0,1]
	v_pk_add_f32 v[248:249], v[142:143], v[72:73] neg_lo:[0,1] neg_hi:[0,1]
	v_pk_add_f32 v[250:251], v[142:143], v[74:75] neg_lo:[0,1] neg_hi:[0,1]
	v_mov_b32_e32 v234, s5
	v_sub_f32_e32 v234, s4, v234
	v_add_f32_e32 v231, v227, v234
	v_add_f32_e32 v230, v226, v234
	v_exp_f32_e64 v232, -v234
	v_pk_add_f32 v[116:117], v[116:117], v[230:231] op_sel:[0,1] op_sel_hi:[1,1] neg_lo:[0,1] neg_hi:[0,1]
	v_pk_add_f32 v[118:119], v[118:119], v[230:231] op_sel:[0,1] op_sel_hi:[1,1] neg_lo:[0,1] neg_hi:[0,1]
	v_pk_add_f32 v[100:101], v[100:101], v[230:231] op_sel_hi:[1,0] neg_lo:[0,1] neg_hi:[0,1]
	v_pk_add_f32 v[102:103], v[102:103], v[230:231] op_sel_hi:[1,0] neg_lo:[0,1] neg_hi:[0,1]
	v_pk_add_f32 v[112:113], v[112:113], v[230:231] op_sel:[0,1] op_sel_hi:[1,1] neg_lo:[0,1] neg_hi:[0,1]
	v_pk_add_f32 v[114:115], v[114:115], v[230:231] op_sel:[0,1] op_sel_hi:[1,1] neg_lo:[0,1] neg_hi:[0,1]
	v_pk_add_f32 v[96:97], v[96:97], v[230:231] op_sel_hi:[1,0] neg_lo:[0,1] neg_hi:[0,1]
	v_pk_add_f32 v[98:99], v[98:99], v[230:231] op_sel_hi:[1,0] neg_lo:[0,1] neg_hi:[0,1]
	v_pk_add_f32 v[108:109], v[108:109], v[230:231] op_sel:[0,1] op_sel_hi:[1,1] neg_lo:[0,1] neg_hi:[0,1]
	v_pk_add_f32 v[110:111], v[110:111], v[230:231] op_sel:[0,1] op_sel_hi:[1,1] neg_lo:[0,1] neg_hi:[0,1]
	v_pk_add_f32 v[244:245], v[244:245], v[230:231] op_sel_hi:[1,0] neg_lo:[0,1] neg_hi:[0,1]
	v_pk_add_f32 v[246:247], v[246:247], v[230:231] op_sel_hi:[1,0] neg_lo:[0,1] neg_hi:[0,1]
	v_pk_add_f32 v[104:105], v[104:105], v[230:231] op_sel:[0,1] op_sel_hi:[1,1] neg_lo:[0,1] neg_hi:[0,1]
	v_pk_add_f32 v[106:107], v[106:107], v[230:231] op_sel:[0,1] op_sel_hi:[1,1] neg_lo:[0,1] neg_hi:[0,1]
	v_pk_add_f32 v[248:249], v[248:249], v[230:231] op_sel_hi:[1,0] neg_lo:[0,1] neg_hi:[0,1]
	v_pk_add_f32 v[250:251], v[250:251], v[230:231] op_sel_hi:[1,0] neg_lo:[0,1] neg_hi:[0,1]
	s_waitcnt lgkmcnt(4)
	v_mfma_f32_16x16x32_bf16 v[116:119], v[88:91], v[0:3], v[116:119]
	v_mfma_f32_16x16x32_bf16 v[100:103], v[88:91], v[8:11], v[100:103]
	v_mfma_f32_16x16x32_bf16 v[112:115], v[164:167], v[0:3], v[112:115]
	v_mfma_f32_16x16x32_bf16 v[96:99], v[164:167], v[8:11], v[96:99]
	v_mfma_f32_16x16x32_bf16 v[116:119], v[92:95], v[4:7], v[116:119]
	v_mfma_f32_16x16x32_bf16 v[100:103], v[92:95], v[12:15], v[100:103]
	v_mfma_f32_16x16x32_bf16 v[112:115], v[168:171], v[4:7], v[112:115]
	v_mfma_f32_16x16x32_bf16 v[96:99], v[168:171], v[12:15], v[96:99]
	s_waitcnt lgkmcnt(0)
	v_mfma_f32_16x16x32_bf16 v[108:111], v[172:175], v[0:3], v[108:111]
	v_mfma_f32_16x16x32_bf16 v[244:247], v[172:175], v[8:11], v[244:247]
	v_mfma_f32_16x16x32_bf16 v[104:107], v[240:243], v[0:3], v[104:107]
	v_mfma_f32_16x16x32_bf16 v[248:251], v[240:243], v[8:11], v[248:251]
	v_mfma_f32_16x16x32_bf16 v[108:111], v[236:239], v[4:7], v[108:111]
	v_mfma_f32_16x16x32_bf16 v[244:247], v[236:239], v[12:15], v[244:247]
	v_mfma_f32_16x16x32_bf16 v[104:107], v[160:163], v[4:7], v[104:107]
	v_mfma_f32_16x16x32_bf16 v[248:251], v[160:163], v[12:15], v[248:251]
	ds_read_b128 v[88:91], v222 offset:9216
	ds_read_b128 v[92:95], v222 offset:9280
	ds_read_b128 v[164:167], v222 offset:11520
	ds_read_b128 v[168:171], v222 offset:11584
	ds_read_b128 v[172:175], v222 offset:13824
	ds_read_b128 v[236:239], v222 offset:13888
	ds_read_b128 v[240:243], v223 offset:9216
	ds_read_b128 v[160:163], v223 offset:9280
	v_max3_f32 v228, v116, v117, v118
	v_max3_f32 v229, v100, v101, v102
	v_max3_f32 v228, v228, v119, v112
	v_max3_f32 v229, v229, v103, v96
	v_max3_f32 v228, v228, v113, v114
	v_max3_f32 v229, v229, v97, v98
	v_max3_f32 v228, v228, v115, v108
	v_max3_f32 v229, v229, v99, v244
	v_max3_f32 v228, v228, v109, v110
	v_max3_f32 v229, v229, v245, v246
	v_max3_f32 v228, v228, v111, v104
	v_max3_f32 v229, v229, v247, v248
	v_max3_f32 v228, v228, v105, v106
	v_max3_f32 v229, v229, v249, v250
	v_max_f32_e32 v228, v228, v107
	v_max_f32_e32 v229, v229, v251
	v_max_f32_e32 v202, v228, v229
	v_cmp_lt_f32_e32 vcc, 0x42800000, v202
	s_cbranch_vccnz .Lattn_orig
	v_mov_b32_e32 v226, v230
	v_mov_b32_e32 v227, v231
	v_pk_mul_f32 v[52:53], v[52:53], v[232:233] op_sel_hi:[1,0]
	v_pk_mul_f32 v[54:55], v[54:55], v[232:233] op_sel_hi:[1,0]
	v_pk_mul_f32 v[44:45], v[44:45], v[232:233] op_sel_hi:[1,0]
	v_pk_mul_f32 v[46:47], v[46:47], v[232:233] op_sel_hi:[1,0]
	v_pk_mul_f32 v[40:41], v[40:41], v[232:233] op_sel_hi:[1,0]
	v_pk_mul_f32 v[42:43], v[42:43], v[232:233] op_sel_hi:[1,0]
	v_pk_mul_f32 v[48:49], v[48:49], v[232:233] op_sel_hi:[1,0]
	v_pk_mul_f32 v[50:51], v[50:51], v[232:233] op_sel_hi:[1,0]
	v_pk_mul_f32 v[36:37], v[36:37], v[232:233] op_sel_hi:[1,0]
	v_pk_mul_f32 v[38:39], v[38:39], v[232:233] op_sel_hi:[1,0]
	v_pk_mul_f32 v[28:29], v[28:29], v[232:233] op_sel_hi:[1,0]
	v_pk_mul_f32 v[30:31], v[30:31], v[232:233] op_sel_hi:[1,0]
	v_pk_mul_f32 v[16:17], v[16:17], v[232:233] op_sel_hi:[1,0]
	v_pk_mul_f32 v[18:19], v[18:19], v[232:233] op_sel_hi:[1,0]
	v_pk_mul_f32 v[32:33], v[32:33], v[232:233] op_sel_hi:[1,0]
	v_pk_mul_f32 v[34:35], v[34:35], v[232:233] op_sel_hi:[1,0]
	v_exp_f32_e32 v116, v116
	v_exp_f32_e32 v117, v117
	v_exp_f32_e32 v118, v118
	v_exp_f32_e32 v119, v119
	v_exp_f32_e32 v112, v112
	v_exp_f32_e32 v113, v113
	v_exp_f32_e32 v114, v114
	v_exp_f32_e32 v115, v115
	v_exp_f32_e32 v108, v108
	v_exp_f32_e32 v109, v109
	v_exp_f32_e32 v110, v110
	v_exp_f32_e32 v111, v111
	v_exp_f32_e32 v104, v104
	v_exp_f32_e32 v105, v105
	v_exp_f32_e32 v106, v106
	v_exp_f32_e32 v107, v107
	v_exp_f32_e32 v100, v100
	v_exp_f32_e32 v101, v101
	v_exp_f32_e32 v102, v102
	v_exp_f32_e32 v103, v103
	v_exp_f32_e32 v96, v96
	v_exp_f32_e32 v97, v97
	v_exp_f32_e32 v98, v98
	v_exp_f32_e32 v99, v99
	v_exp_f32_e32 v244, v244
	v_exp_f32_e32 v245, v245
	v_exp_f32_e32 v246, v246
	v_exp_f32_e32 v247, v247
	v_exp_f32_e32 v248, v248
	v_exp_f32_e32 v249, v249
	v_exp_f32_e32 v250, v250
	v_exp_f32_e32 v251, v251
	v_add_f32_e32 v228, 0, v116
	v_add_f32_e32 v229, 0, v100
	v_add_f32_e32 v228, v117, v228
	v_add_f32_e32 v229, v101, v229
	v_add_f32_e32 v228, v118, v228
	v_add_f32_e32 v229, v102, v229
	v_add_f32_e32 v228, v119, v228
	v_add_f32_e32 v229, v103, v229
	v_add_f32_e32 v228, v112, v228
	v_add_f32_e32 v229, v96, v229
	v_add_f32_e32 v228, v113, v228
	v_add_f32_e32 v229, v97, v229
	v_add_f32_e32 v228, v114, v228
	v_add_f32_e32 v229, v98, v229
	v_add_f32_e32 v228, v115, v228
	v_add_f32_e32 v229, v99, v229
	v_add_f32_e32 v228, v108, v228
	v_add_f32_e32 v229, v244, v229
	v_add_f32_e32 v228, v109, v228
	v_add_f32_e32 v229, v245, v229
	v_add_f32_e32 v228, v110, v228
	v_add_f32_e32 v229, v246, v229
	v_add_f32_e32 v228, v111, v228
	v_add_f32_e32 v229, v247, v229
	v_add_f32_e32 v228, v104, v228
	v_add_f32_e32 v229, v248, v229
	v_add_f32_e32 v228, v105, v228
	v_add_f32_e32 v229, v249, v229
	v_add_f32_e32 v228, v106, v228
	v_add_f32_e32 v229, v250, v229
	v_add_f32_e32 v228, v107, v228
	v_add_f32_e32 v229, v251, v229
	v_cvt_pk_bf16_f32 v76, v116, v117
	v_cvt_pk_bf16_f32 v77, v118, v119
	v_cvt_pk_bf16_f32 v78, v112, v113
	v_cvt_pk_bf16_f32 v79, v114, v115
	v_cvt_pk_bf16_f32 v84, v100, v101
	v_cvt_pk_bf16_f32 v85, v102, v103
	v_cvt_pk_bf16_f32 v86, v96, v97
	v_cvt_pk_bf16_f32 v87, v98, v99
	v_cvt_pk_bf16_f32 v72, v108, v109
	v_cvt_pk_bf16_f32 v73, v110, v111
	v_cvt_pk_bf16_f32 v74, v104, v105
	v_cvt_pk_bf16_f32 v75, v106, v107
	v_cvt_pk_bf16_f32 v80, v244, v245
	v_cvt_pk_bf16_f32 v81, v246, v247
	v_cvt_pk_bf16_f32 v82, v248, v249
	v_cvt_pk_bf16_f32 v83, v250, v251
	v_fma_f32 v225, v225, v232, v228
	v_fma_f32 v224, v224, v232, v229
	s_nop 1
	s_waitcnt lgkmcnt(7)
	v_mfma_f32_16x16x32_bf16 v[52:55], v[88:91], v[76:79], v[52:55]
	v_mfma_f32_16x16x32_bf16 v[36:39], v[88:91], v[84:87], v[36:39]
	s_waitcnt lgkmcnt(6)
	v_mfma_f32_16x16x32_bf16 v[52:55], v[92:95], v[72:75], v[52:55]
	v_mfma_f32_16x16x32_bf16 v[36:39], v[92:95], v[80:83], v[36:39]
	s_waitcnt lgkmcnt(5)
	v_mfma_f32_16x16x32_bf16 v[44:47], v[164:167], v[76:79], v[44:47]
	v_mfma_f32_16x16x32_bf16 v[28:31], v[164:167], v[84:87], v[28:31]
	s_waitcnt lgkmcnt(4)
	v_mfma_f32_16x16x32_bf16 v[44:47], v[168:171], v[72:75], v[44:47]
	v_mfma_f32_16x16x32_bf16 v[28:31], v[168:171], v[80:83], v[28:31]
	s_waitcnt lgkmcnt(3)
	v_mfma_f32_16x16x32_bf16 v[40:43], v[172:175], v[76:79], v[40:43]
	v_mfma_f32_16x16x32_bf16 v[16:19], v[172:175], v[84:87], v[16:19]
	s_waitcnt lgkmcnt(2)
	v_mfma_f32_16x16x32_bf16 v[40:43], v[236:239], v[72:75], v[40:43]
	v_mfma_f32_16x16x32_bf16 v[16:19], v[236:239], v[80:83], v[16:19]
	s_waitcnt lgkmcnt(1)
	v_mfma_f32_16x16x32_bf16 v[48:51], v[240:243], v[76:79], v[48:51]
	v_mfma_f32_16x16x32_bf16 v[32:35], v[240:243], v[84:87], v[32:35]
	s_waitcnt lgkmcnt(0)
	v_mfma_f32_16x16x32_bf16 v[48:51], v[160:163], v[72:75], v[48:51]
	v_mfma_f32_16x16x32_bf16 v[32:35], v[160:163], v[80:83], v[32:35]
	s_branch .LBB0_883
